# hoist compiler vmcnt(0) out of in-proj and up GEMM K-loops (once per unit instead of per iteration)
# speedup vs baseline: 1.0010x; 1.0010x over previous
; #define PG8_STAGE(bufoff, gbase, voff) do { _Pragma("unroll") for (int _i = 0; _i < 2; ++_i) \
;         __builtin_amdgcn_global_load_lds((const unsigned*)((const char*)(gbase) + (voff)[_i]), (PG8_LAS unsigned*)(lds + (bufoff) + ldsw + _i * 8192), 16, 0, 0); } while (0)
; #define PG8_LDA(dst, b, h) do { _Pragma("unroll") for (int m = 0; m < 4; ++m) _Pragma("unroll") for (int k = 0; k < 2; ++k) dst[m][k] = *(const PG8_LAS bf16x8*)(lds + PG8_SA(b, h) + aoff + m * 2048 + k * 1024); } while (0)
; #define PG8_LDB(dst, b, h) do { _Pragma("unroll") for (int n = 0; n < 2; ++n) _Pragma("unroll") for (int k = 0; k < 2; ++k) dst[n][k] = *(const PG8_LAS bf16x8*)(lds + PG8_SB(b, h) + boff + n * 2048 + k * 1024); } while (0)
; #define PG8_WAIT_V(n) asm volatile("s_waitcnt vmcnt(" #n ")" ::: "memory")
; #define PG8_WAIT_L(n) asm volatile("s_waitcnt lgkmcnt(" #n ")" ::: "memory")
; #define PG8_BAR __builtin_amdgcn_s_barrier()
; template <class Epi, class Sched, bool ALIGN_EPI = false, bool SP2 = false, bool HALO = false>
; __device__ __forceinline__ void gemm_phase(PG8_LAS unsigned char* lds, const Gemm g, const Sched& S, const Epi& E, const int wave0) {
;     ...
;         const bool has_next = S.next(ui + 1, nxt);
;         const char* nA = has_next ? (const char*)g.A + (size_t)nxt.pm * tstepA : cA; const char* nB = has_next ? (const char*)g.Bt + (size_t)nxt.pn * tstep : cB;
;         for (int t = 0; t < nt; t += 2) {
;             const bool last = (t == nt - 2);
;             const char* a1 = cA + (size_t)(t + 1) * kstep;
;             const char* a2 = last ? nA : cA + (size_t)(t + 2) * kstep; const char* b2 = last ? nB : cB + (size_t)(t + 2) * kstep;
;             const char* a3 = a2 + kstep; const char* b3 = b2 + kstep;
;             if (last && has_next) S.a_ready(nxt);
;             if constexpr (SP2) {
;             PG8_LDB(B0, 0, 0); PG8_LDB(B1, 0, 1); PG8_SCHED; PG8_LDA(At, 0, 0); PG8_STAGE(PG8_SA(1, 1), a1 + hstepA, voffA);
;             PG8_WAIT_V(8); PG8_WAIT_L(0); PG8_BAR; PG8_MMA(0, 0, At, B0); PG8_MMA(0, 1, At, B1); PG8_BAR; PG8_SCHED;
;     ...
;         for (int a = 0; a < 2; ++a)
; #pragma unroll
;             for (int b = 0; b < 2; ++b)
; #pragma unroll
;                 for (int m = 0; m < 4; ++m)
; #pragma unroll
;                     for (int n = 0; n < 2; ++n) acc[a][b][m][n] = (f32x4){0.f, 0.f, 0.f, 0.f};
;         cur = nxt; cA = nA; cB = nB; ++ui;
.LBB0_277:
	s_ashr_i32 s75, s74, 31
	s_lshl_b64 s[4:5], s[74:75], 19
	s_add_u32 s76, s65, s4
	s_addc_u32 s77, s12, s5
	s_and_b64 s[4:5], s[36:37], exec
	s_cselect_b32 s4, s77, s45
	s_cselect_b32 s5, s76, s44
	s_ashr_i32 s73, s72, 31
	s_lshl_b64 s[14:15], s[72:73], 19
	s_add_u32 s86, s13, s14
	s_addc_u32 s87, s80, s15
	s_and_b64 s[14:15], s[36:37], exec
	s_cselect_b32 s10, s87, s43
	s_cselect_b32 s39, s86, s42
	s_add_u32 s41, s42, 0x100
	s_addc_u32 s66, s43, 0
	s_add_u32 s42, s44, 0x40080
	v_mov_b32_e32 v0, 0
	s_addc_u32 s43, s45, 0
	s_mov_b32 s67, -2
	v_mov_b32_e32 v1, v0
	v_mov_b32_e32 v2, v0
	v_mov_b32_e32 v3, v0
	v_mov_b32_e32 v4, v0
	v_mov_b32_e32 v5, v0
	v_mov_b32_e32 v6, v0
	v_mov_b32_e32 v7, v0
	v_mov_b32_e32 v16, v0
	v_mov_b32_e32 v17, v0
	v_mov_b32_e32 v18, v0
	v_mov_b32_e32 v19, v0
	v_mov_b32_e32 v20, v0
	v_mov_b32_e32 v21, v0
	v_mov_b32_e32 v22, v0
	v_mov_b32_e32 v23, v0
	v_mov_b32_e32 v32, v0
	v_mov_b32_e32 v33, v0
	v_mov_b32_e32 v34, v0
	v_mov_b32_e32 v35, v0
	v_mov_b32_e32 v36, v0
	v_mov_b32_e32 v37, v0
	v_mov_b32_e32 v38, v0
	v_mov_b32_e32 v39, v0
	v_mov_b32_e32 v64, v0
	v_mov_b32_e32 v65, v0
	v_mov_b32_e32 v66, v0
	v_mov_b32_e32 v67, v0
	v_mov_b32_e32 v68, v0
	v_mov_b32_e32 v69, v0
	v_mov_b32_e32 v70, v0
	v_mov_b32_e32 v71, v0
	v_mov_b32_e32 v8, v0
	v_mov_b32_e32 v9, v0
	v_mov_b32_e32 v10, v0
	v_mov_b32_e32 v11, v0
	v_mov_b32_e32 v12, v0
	v_mov_b32_e32 v13, v0
	v_mov_b32_e32 v14, v0
	v_mov_b32_e32 v15, v0
	v_mov_b32_e32 v24, v0
	v_mov_b32_e32 v25, v0
	v_mov_b32_e32 v26, v0
	v_mov_b32_e32 v27, v0
	v_mov_b32_e32 v28, v0
	v_mov_b32_e32 v29, v0
	v_mov_b32_e32 v30, v0
	v_mov_b32_e32 v31, v0
	v_mov_b32_e32 v40, v0
	v_mov_b32_e32 v41, v0
	v_mov_b32_e32 v42, v0
	v_mov_b32_e32 v43, v0
	v_mov_b32_e32 v44, v0
	v_mov_b32_e32 v45, v0
	v_mov_b32_e32 v46, v0
	v_mov_b32_e32 v47, v0
	v_mov_b32_e32 v72, v0
	v_mov_b32_e32 v73, v0
	v_mov_b32_e32 v74, v0
	v_mov_b32_e32 v75, v0
	v_mov_b32_e32 v76, v0
	v_mov_b32_e32 v77, v0
	v_mov_b32_e32 v78, v0
	v_mov_b32_e32 v79, v0
	v_mov_b32_e32 v80, v0
	v_mov_b32_e32 v81, v0
	v_mov_b32_e32 v82, v0
	v_mov_b32_e32 v83, v0
	v_mov_b32_e32 v84, v0
	v_mov_b32_e32 v85, v0
	v_mov_b32_e32 v86, v0
	v_mov_b32_e32 v87, v0
	v_mov_b32_e32 v96, v0
	v_mov_b32_e32 v97, v0
	v_mov_b32_e32 v98, v0
	v_mov_b32_e32 v99, v0
	v_mov_b32_e32 v100, v0
	v_mov_b32_e32 v101, v0
	v_mov_b32_e32 v102, v0
	v_mov_b32_e32 v103, v0
	v_mov_b32_e32 v112, v0
	v_mov_b32_e32 v113, v0
	v_mov_b32_e32 v114, v0
	v_mov_b32_e32 v115, v0
	v_mov_b32_e32 v116, v0
	v_mov_b32_e32 v117, v0
	v_mov_b32_e32 v118, v0
	v_mov_b32_e32 v119, v0
	v_mov_b32_e32 v128, v0
	v_mov_b32_e32 v129, v0
	v_mov_b32_e32 v130, v0
	v_mov_b32_e32 v131, v0
	v_mov_b32_e32 v132, v0
	v_mov_b32_e32 v133, v0
	v_mov_b32_e32 v134, v0
	v_mov_b32_e32 v135, v0
	v_mov_b32_e32 v88, v0
	v_mov_b32_e32 v89, v0
	v_mov_b32_e32 v90, v0
	v_mov_b32_e32 v91, v0
	v_mov_b32_e32 v92, v0
	v_mov_b32_e32 v93, v0
	v_mov_b32_e32 v94, v0
	v_mov_b32_e32 v95, v0
	v_mov_b32_e32 v104, v0
	v_mov_b32_e32 v105, v0
	v_mov_b32_e32 v106, v0
	v_mov_b32_e32 v107, v0
	v_mov_b32_e32 v108, v0
	v_mov_b32_e32 v109, v0
	v_mov_b32_e32 v110, v0
	v_mov_b32_e32 v111, v0
	v_mov_b32_e32 v120, v0
	v_mov_b32_e32 v121, v0
	v_mov_b32_e32 v122, v0
	v_mov_b32_e32 v123, v0
	v_mov_b32_e32 v124, v0
	v_mov_b32_e32 v125, v0
	v_mov_b32_e32 v126, v0
	v_mov_b32_e32 v127, v0
	v_mov_b32_e32 v136, v0
	v_mov_b32_e32 v137, v0
	v_mov_b32_e32 v138, v0
	v_mov_b32_e32 v139, v0
	v_mov_b32_e32 v140, v0
	v_mov_b32_e32 v141, v0
	v_mov_b32_e32 v142, v0
	v_mov_b32_e32 v143, v0
	s_waitcnt vmcnt(0)
.LBB0_278:
	s_add_u32 s14, s42, 0xfffc0080
	s_addc_u32 s15, s43, -1
	s_add_i32 s70, 0, 0x10000
	s_cmp_eq_u32 s67, 12
	s_cselect_b32 s45, s4, s15
	s_cselect_b32 s44, s5, s14
	s_cselect_b32 s15, s10, s66
	s_cselect_b32 s14, s39, s41
	s_add_i32 s73, 0, 0x14000
	v_add_u32_e32 v60, s70, v194
	v_add_u32_e32 v172, s73, v194
	ds_read_b128 v[48:51], v60
	ds_read_b128 v[52:55], v60 offset:1024
	ds_read_b128 v[56:59], v60 offset:2048
	ds_read_b128 v[60:63], v60 offset:3072
	ds_read_b128 v[160:163], v172
	ds_read_b128 v[164:167], v172 offset:1024
	ds_read_b128 v[168:171], v172 offset:2048
	ds_read_b128 v[172:175], v172 offset:3072
	v_lshl_add_u64 v[192:193], s[42:43], 0, v[158:159]
	s_add_i32 m0, s23, 0xc000
	ds_read_b128 v[176:179], v199
	ds_read_b128 v[180:183], v199 offset:1024
	ds_read_b128 v[184:187], v199 offset:2048
	ds_read_b128 v[188:191], v199 offset:3072
	ds_read_b128 v[200:203], v199 offset:4096
	ds_read_b128 v[204:207], v199 offset:5120
	ds_read_b128 v[210:213], v199 offset:6144
	ds_read_b128 v[244:247], v199 offset:7168
	global_load_lds_dwordx4 v[192:193], off
	v_lshl_add_u64 v[192:193], s[42:43], 0, v[156:157]
	s_add_i32 m0, s23, 0xe000
	s_nop 0
	global_load_lds_dwordx4 v[192:193], off
	s_waitcnt vmcnt(8)
	s_waitcnt lgkmcnt(0)
	s_barrier
; #define PG8_STAGE(bufoff, gbase, voff) do { _Pragma("unroll") for (int _i = 0; _i < 2; ++_i) \
;         __builtin_amdgcn_global_load_lds((const unsigned*)((const char*)(gbase) + (voff)[_i]), (PG8_LAS unsigned*)(lds + (bufoff) + ldsw + _i * 8192), 16, 0, 0); } while (0)
; #define PG8_LDA(dst, b, h) do { _Pragma("unroll") for (int m = 0; m < 4; ++m) _Pragma("unroll") for (int k = 0; k < 2; ++k) dst[m][k] = *(const PG8_LAS bf16x8*)(lds + PG8_SA(b, h) + aoff + m * 2048 + k * 1024); } while (0)
; #define PG8_MMA(ai, bj, At, Bt) do { __builtin_amdgcn_s_setprio(1); _Pragma("unroll") for (int m = 0; m < 4; ++m) _Pragma("unroll") for (int n = 0; n < 2; ++n) _Pragma("unroll") for (int k = 0; k < 2; ++k) \
;         acc[ai][bj][m][n] = __builtin_amdgcn_mfma_f32_16x16x32_bf16(Bt[n][k], At[m][k], acc[ai][bj][m][n], 0, 0, 0); __builtin_amdgcn_s_setprio(0); } while (0)
; #define PG8_WAIT_V(n) asm volatile("s_waitcnt vmcnt(" #n ")" ::: "memory")
; #define PG8_WAIT_L(n) asm volatile("s_waitcnt lgkmcnt(" #n ")" ::: "memory")
; #define PG8_BAR __builtin_amdgcn_s_barrier()
; #define PG8_SCHED __builtin_amdgcn_sched_barrier(0)
; template <class Epi, class Sched, bool ALIGN_EPI = false, bool SP2 = false, bool HALO = false>
; __device__ __forceinline__ void gemm_phase(PG8_LAS unsigned char* lds, const Gemm g, const Sched& S, const Epi& E, const int wave0) {
;     ...
;             PG8_WAIT_V(8); PG8_WAIT_L(0); PG8_BAR; PG8_MMA(0, 0, At, B0); PG8_MMA(0, 1, At, B1); PG8_BAR; PG8_SCHED;
;             PG8_LDA(At, 0, 1); PG8_STAGE(PG8_SB(0, 0), b2, voffB); PG8_STAGE(PG8_SB(0, 1), b2 + hstep, voffB); PG8_STAGE(PG8_SA(0, 0), a2, voffA);
;             PG8_WAIT_V(8); PG8_WAIT_L(0); PG8_BAR; PG8_MMA(1, 0, At, B0); PG8_MMA(1, 1, At, B1); PG8_BAR; PG8_SCHED;
	s_setprio 1
	s_waitcnt lgkmcnt(0)
	v_mfma_f32_16x16x32_bf16 v[140:143], v[48:51], v[176:179], v[140:143]
	v_mfma_f32_16x16x32_bf16 v[136:139], v[56:59], v[176:179], v[136:139]
	v_mfma_f32_16x16x32_bf16 v[124:127], v[48:51], v[184:187], v[124:127]
	v_mfma_f32_16x16x32_bf16 v[120:123], v[56:59], v[184:187], v[120:123]
	v_mfma_f32_16x16x32_bf16 v[108:111], v[48:51], v[200:203], v[108:111]
	v_mfma_f32_16x16x32_bf16 v[104:107], v[56:59], v[200:203], v[104:107]
	v_mfma_f32_16x16x32_bf16 v[92:95], v[48:51], v[210:213], v[92:95]
	v_mfma_f32_16x16x32_bf16 v[88:91], v[56:59], v[210:213], v[88:91]
	v_mfma_f32_16x16x32_bf16 v[140:143], v[52:55], v[180:183], v[140:143]
	v_mfma_f32_16x16x32_bf16 v[136:139], v[60:63], v[180:183], v[136:139]
	v_mfma_f32_16x16x32_bf16 v[124:127], v[52:55], v[188:191], v[124:127]
	v_mfma_f32_16x16x32_bf16 v[120:123], v[60:63], v[188:191], v[120:123]
	v_mfma_f32_16x16x32_bf16 v[108:111], v[52:55], v[204:207], v[108:111]
	v_mfma_f32_16x16x32_bf16 v[104:107], v[60:63], v[204:207], v[104:107]
	v_mfma_f32_16x16x32_bf16 v[92:95], v[52:55], v[244:247], v[92:95]
	v_mfma_f32_16x16x32_bf16 v[88:91], v[60:63], v[244:247], v[88:91]
	s_setprio 0
	s_setprio 1
	v_mfma_f32_16x16x32_bf16 v[132:135], v[160:163], v[176:179], v[132:135]
	v_mfma_f32_16x16x32_bf16 v[128:131], v[168:171], v[176:179], v[128:131]
	v_mfma_f32_16x16x32_bf16 v[116:119], v[160:163], v[184:187], v[116:119]
	v_mfma_f32_16x16x32_bf16 v[112:115], v[168:171], v[184:187], v[112:115]
	v_mfma_f32_16x16x32_bf16 v[100:103], v[160:163], v[200:203], v[100:103]
	v_mfma_f32_16x16x32_bf16 v[96:99], v[168:171], v[200:203], v[96:99]
	v_mfma_f32_16x16x32_bf16 v[84:87], v[160:163], v[210:213], v[84:87]
	v_mfma_f32_16x16x32_bf16 v[80:83], v[168:171], v[210:213], v[80:83]
	v_mfma_f32_16x16x32_bf16 v[132:135], v[164:167], v[180:183], v[132:135]
	v_mfma_f32_16x16x32_bf16 v[128:131], v[172:175], v[180:183], v[128:131]
	v_mfma_f32_16x16x32_bf16 v[116:119], v[164:167], v[188:191], v[116:119]
	v_mfma_f32_16x16x32_bf16 v[112:115], v[172:175], v[188:191], v[112:115]
	v_mfma_f32_16x16x32_bf16 v[100:103], v[164:167], v[204:207], v[100:103]
	v_mfma_f32_16x16x32_bf16 v[96:99], v[172:175], v[204:207], v[96:99]
	v_mfma_f32_16x16x32_bf16 v[84:87], v[164:167], v[244:247], v[84:87]
	v_mfma_f32_16x16x32_bf16 v[80:83], v[172:175], v[244:247], v[80:83]
	s_setprio 0
	s_barrier
	s_add_i32 s70, s70, s81
	v_lshl_add_u64 v[192:193], s[14:15], 0, v[146:147]
	s_mov_b32 m0, s70
	ds_read_b128 v[176:179], v199 offset:16384
	ds_read_b128 v[180:183], v199 offset:17408
	ds_read_b128 v[184:187], v199 offset:18432
	ds_read_b128 v[188:191], v199 offset:19456
	ds_read_b128 v[200:203], v199 offset:20480
	ds_read_b128 v[204:207], v199 offset:21504
	ds_read_b128 v[210:213], v199 offset:22528
	ds_read_b128 v[244:247], v199 offset:23552
	global_load_lds_dwordx4 v[192:193], off
	s_add_i32 m0, s70, 0x2000
	s_add_u32 s70, s14, 0x40000
	v_lshl_add_u64 v[214:215], s[14:15], 0, v[150:151]
	s_addc_u32 s71, s15, 0
	s_add_i32 s73, s73, s81
	global_load_lds_dwordx4 v[214:215], off
	v_lshl_add_u64 v[248:249], s[70:71], 0, v[146:147]
	s_mov_b32 m0, s73
	v_lshl_add_u64 v[250:251], s[44:45], 0, v[148:149]
	global_load_lds_dwordx4 v[248:249], off
	v_lshl_add_u64 v[248:249], s[70:71], 0, v[150:151]
	s_add_i32 m0, s73, 0x2000
	s_nop 0
	global_load_lds_dwordx4 v[248:249], off
	v_lshl_add_u64 v[248:249], s[44:45], 0, v[144:145]
	s_mov_b32 m0, s23
	s_nop 0
	global_load_lds_dwordx4 v[248:249], off
	s_mov_b32 m0, s34
	s_nop 0
	global_load_lds_dwordx4 v[250:251], off
	s_waitcnt vmcnt(8)
	s_waitcnt lgkmcnt(0)
	s_barrier
	s_setprio 1
	s_waitcnt lgkmcnt(0)
	v_mfma_f32_16x16x32_bf16 v[76:79], v[48:51], v[176:179], v[76:79]
	v_mfma_f32_16x16x32_bf16 v[72:75], v[56:59], v[176:179], v[72:75]
	v_mfma_f32_16x16x32_bf16 v[44:47], v[48:51], v[184:187], v[44:47]
	v_mfma_f32_16x16x32_bf16 v[40:43], v[56:59], v[184:187], v[40:43]
	v_mfma_f32_16x16x32_bf16 v[28:31], v[48:51], v[200:203], v[28:31]
	v_mfma_f32_16x16x32_bf16 v[24:27], v[56:59], v[200:203], v[24:27]
	v_mfma_f32_16x16x32_bf16 v[12:15], v[48:51], v[210:213], v[12:15]
	v_mfma_f32_16x16x32_bf16 v[8:11], v[56:59], v[210:213], v[8:11]
	v_mfma_f32_16x16x32_bf16 v[76:79], v[52:55], v[180:183], v[76:79]
	v_mfma_f32_16x16x32_bf16 v[72:75], v[60:63], v[180:183], v[72:75]
	v_mfma_f32_16x16x32_bf16 v[44:47], v[52:55], v[188:191], v[44:47]
	v_mfma_f32_16x16x32_bf16 v[40:43], v[60:63], v[188:191], v[40:43]
	v_mfma_f32_16x16x32_bf16 v[28:31], v[52:55], v[204:207], v[28:31]
	v_mfma_f32_16x16x32_bf16 v[24:27], v[60:63], v[204:207], v[24:27]
	v_mfma_f32_16x16x32_bf16 v[12:15], v[52:55], v[244:247], v[12:15]
	v_mfma_f32_16x16x32_bf16 v[8:11], v[60:63], v[244:247], v[8:11]
	s_setprio 0
	s_setprio 1
	v_mfma_f32_16x16x32_bf16 v[36:39], v[160:163], v[184:187], v[36:39]
	v_mfma_f32_16x16x32_bf16 v[32:35], v[168:171], v[184:187], v[32:35]
	v_mfma_f32_16x16x32_bf16 v[20:23], v[160:163], v[200:203], v[20:23]
	v_mfma_f32_16x16x32_bf16 v[16:19], v[168:171], v[200:203], v[16:19]
	v_mfma_f32_16x16x32_bf16 v[4:7], v[160:163], v[210:213], v[4:7]
	v_mfma_f32_16x16x32_bf16 v[0:3], v[168:171], v[210:213], v[0:3]
	v_mfma_f32_16x16x32_bf16 v[48:51], v[160:163], v[176:179], v[68:71]
	v_mfma_f32_16x16x32_bf16 v[52:55], v[168:171], v[176:179], v[64:67]
	v_mfma_f32_16x16x32_bf16 v[36:39], v[164:167], v[188:191], v[36:39]
	v_mfma_f32_16x16x32_bf16 v[32:35], v[172:175], v[188:191], v[32:35]
	v_mfma_f32_16x16x32_bf16 v[20:23], v[164:167], v[204:207], v[20:23]
	v_mfma_f32_16x16x32_bf16 v[16:19], v[172:175], v[204:207], v[16:19]
	v_mfma_f32_16x16x32_bf16 v[4:7], v[164:167], v[244:247], v[4:7]
	v_mfma_f32_16x16x32_bf16 v[0:3], v[172:175], v[244:247], v[0:3]
	v_mfma_f32_16x16x32_bf16 v[48:51], v[164:167], v[180:183], v[48:51]
	v_mfma_f32_16x16x32_bf16 v[52:55], v[172:175], v[180:183], v[52:55]
	s_setprio 0
	s_barrier
; #define PG8_STAGE(bufoff, gbase, voff) do { _Pragma("unroll") for (int _i = 0; _i < 2; ++_i) \
;         __builtin_amdgcn_global_load_lds((const unsigned*)((const char*)(gbase) + (voff)[_i]), (PG8_LAS unsigned*)(lds + (bufoff) + ldsw + _i * 8192), 16, 0, 0); } while (0)
; #define PG8_LDA(dst, b, h) do { _Pragma("unroll") for (int m = 0; m < 4; ++m) _Pragma("unroll") for (int k = 0; k < 2; ++k) dst[m][k] = *(const PG8_LAS bf16x8*)(lds + PG8_SA(b, h) + aoff + m * 2048 + k * 1024); } while (0)
; #define PG8_LDB(dst, b, h) do { _Pragma("unroll") for (int n = 0; n < 2; ++n) _Pragma("unroll") for (int k = 0; k < 2; ++k) dst[n][k] = *(const PG8_LAS bf16x8*)(lds + PG8_SB(b, h) + boff + n * 2048 + k * 1024); } while (0)
; #define PG8_MMA(ai, bj, At, Bt) do { __builtin_amdgcn_s_setprio(1); _Pragma("unroll") for (int m = 0; m < 4; ++m) _Pragma("unroll") for (int n = 0; n < 2; ++n) _Pragma("unroll") for (int k = 0; k < 2; ++k) \
;         acc[ai][bj][m][n] = __builtin_amdgcn_mfma_f32_16x16x32_bf16(Bt[n][k], At[m][k], acc[ai][bj][m][n], 0, 0, 0); __builtin_amdgcn_s_setprio(0); } while (0)
; #define PG8_WAIT_V(n) asm volatile("s_waitcnt vmcnt(" #n ")" ::: "memory")
; #define PG8_WAIT_L(n) asm volatile("s_waitcnt lgkmcnt(" #n ")" ::: "memory")
; #define PG8_BAR __builtin_amdgcn_s_barrier()
; #define PG8_SCHED __builtin_amdgcn_sched_barrier(0)
; template <class Epi, class Sched, bool ALIGN_EPI = false, bool SP2 = false, bool HALO = false>
; __device__ __forceinline__ void gemm_phase(PG8_LAS unsigned char* lds, const Gemm g, const Sched& S, const Epi& E, const int wave0) {
;     ...
;             PG8_LDB(B0, 1, 0); PG8_LDB(B1, 1, 1); PG8_SCHED; PG8_LDA(At, 1, 0); PG8_STAGE(PG8_SA(0, 1), a2 + hstepA, voffA);
;             PG8_WAIT_V(8); PG8_WAIT_L(0); PG8_BAR; PG8_MMA(0, 0, At, B0); PG8_MMA(0, 1, At, B1); PG8_BAR; PG8_SCHED;
	s_add_i32 s70, 0, 0x18000
	s_add_i32 s71, 0, 0x1c000
	v_add_u32_e32 v68, s70, v194
	v_add_u32_e32 v172, s71, v194
	ds_read_b128 v[56:59], v68
	ds_read_b128 v[60:63], v68 offset:1024
	ds_read_b128 v[64:67], v68 offset:2048
	ds_read_b128 v[68:71], v68 offset:3072
	ds_read_b128 v[160:163], v172
	ds_read_b128 v[164:167], v172 offset:1024
	ds_read_b128 v[168:171], v172 offset:2048
	ds_read_b128 v[172:175], v172 offset:3072
	s_add_u32 s44, s44, 0x40000
	s_addc_u32 s45, s45, 0
	s_mov_b32 m0, s35
	v_lshl_add_u64 v[238:239], s[44:45], 0, v[144:145]
	ds_read_b128 v[176:179], v199 offset:32768
	ds_read_b128 v[180:183], v199 offset:33792
	ds_read_b128 v[184:187], v199 offset:34816
	ds_read_b128 v[188:191], v199 offset:35840
	ds_read_b128 v[200:203], v199 offset:36864
	ds_read_b128 v[204:207], v199 offset:37888
	ds_read_b128 v[210:213], v199 offset:38912
	ds_read_b128 v[244:247], v199 offset:39936
	global_load_lds_dwordx4 v[238:239], off
	v_lshl_add_u64 v[238:239], s[44:45], 0, v[148:149]
	s_mov_b32 m0, s88
	s_nop 0
	global_load_lds_dwordx4 v[238:239], off
	s_waitcnt vmcnt(8)
	s_waitcnt lgkmcnt(0)
	s_barrier
	s_setprio 1
	s_waitcnt lgkmcnt(0)
	v_mfma_f32_16x16x32_bf16 v[140:143], v[56:59], v[176:179], v[140:143]
	v_mfma_f32_16x16x32_bf16 v[136:139], v[64:67], v[176:179], v[136:139]
	v_mfma_f32_16x16x32_bf16 v[124:127], v[56:59], v[184:187], v[124:127]
	v_mfma_f32_16x16x32_bf16 v[120:123], v[64:67], v[184:187], v[120:123]
	v_mfma_f32_16x16x32_bf16 v[108:111], v[56:59], v[200:203], v[108:111]
	v_mfma_f32_16x16x32_bf16 v[104:107], v[64:67], v[200:203], v[104:107]
	v_mfma_f32_16x16x32_bf16 v[92:95], v[56:59], v[210:213], v[92:95]
	v_mfma_f32_16x16x32_bf16 v[88:91], v[64:67], v[210:213], v[88:91]
	v_mfma_f32_16x16x32_bf16 v[140:143], v[60:63], v[180:183], v[140:143]
	v_mfma_f32_16x16x32_bf16 v[136:139], v[68:71], v[180:183], v[136:139]
	v_mfma_f32_16x16x32_bf16 v[124:127], v[60:63], v[188:191], v[124:127]
	v_mfma_f32_16x16x32_bf16 v[120:123], v[68:71], v[188:191], v[120:123]
	v_mfma_f32_16x16x32_bf16 v[108:111], v[60:63], v[204:207], v[108:111]
	v_mfma_f32_16x16x32_bf16 v[104:107], v[68:71], v[204:207], v[104:107]
	v_mfma_f32_16x16x32_bf16 v[92:95], v[60:63], v[244:247], v[92:95]
	v_mfma_f32_16x16x32_bf16 v[88:91], v[68:71], v[244:247], v[88:91]
	s_setprio 0
	s_setprio 1
	v_mfma_f32_16x16x32_bf16 v[132:135], v[160:163], v[176:179], v[132:135]
	v_mfma_f32_16x16x32_bf16 v[128:131], v[168:171], v[176:179], v[128:131]
	v_mfma_f32_16x16x32_bf16 v[116:119], v[160:163], v[184:187], v[116:119]
	v_mfma_f32_16x16x32_bf16 v[112:115], v[168:171], v[184:187], v[112:115]
	v_mfma_f32_16x16x32_bf16 v[100:103], v[160:163], v[200:203], v[100:103]
	v_mfma_f32_16x16x32_bf16 v[96:99], v[168:171], v[200:203], v[96:99]
	v_mfma_f32_16x16x32_bf16 v[84:87], v[160:163], v[210:213], v[84:87]
	v_mfma_f32_16x16x32_bf16 v[80:83], v[168:171], v[210:213], v[80:83]
	v_mfma_f32_16x16x32_bf16 v[132:135], v[164:167], v[180:183], v[132:135]
	v_mfma_f32_16x16x32_bf16 v[128:131], v[172:175], v[180:183], v[128:131]
	v_mfma_f32_16x16x32_bf16 v[116:119], v[164:167], v[188:191], v[116:119]
	v_mfma_f32_16x16x32_bf16 v[112:115], v[172:175], v[188:191], v[112:115]
	v_mfma_f32_16x16x32_bf16 v[100:103], v[164:167], v[204:207], v[100:103]
	v_mfma_f32_16x16x32_bf16 v[96:99], v[172:175], v[204:207], v[96:99]
	v_mfma_f32_16x16x32_bf16 v[84:87], v[164:167], v[244:247], v[84:87]
	v_mfma_f32_16x16x32_bf16 v[80:83], v[172:175], v[244:247], v[80:83]
	s_setprio 0
	s_barrier
; #define PG8_STAGE(bufoff, gbase, voff) do { _Pragma("unroll") for (int _i = 0; _i < 2; ++_i) \
;         __builtin_amdgcn_global_load_lds((const unsigned*)((const char*)(gbase) + (voff)[_i]), (PG8_LAS unsigned*)(lds + (bufoff) + ldsw + _i * 8192), 16, 0, 0); } while (0)
; #define PG8_LDA(dst, b, h) do { _Pragma("unroll") for (int m = 0; m < 4; ++m) _Pragma("unroll") for (int k = 0; k < 2; ++k) dst[m][k] = *(const PG8_LAS bf16x8*)(lds + PG8_SA(b, h) + aoff + m * 2048 + k * 1024); } while (0)
; #define PG8_MMA(ai, bj, At, Bt) do { __builtin_amdgcn_s_setprio(1); _Pragma("unroll") for (int m = 0; m < 4; ++m) _Pragma("unroll") for (int n = 0; n < 2; ++n) _Pragma("unroll") for (int k = 0; k < 2; ++k) \
;         acc[ai][bj][m][n] = __builtin_amdgcn_mfma_f32_16x16x32_bf16(Bt[n][k], At[m][k], acc[ai][bj][m][n], 0, 0, 0); __builtin_amdgcn_s_setprio(0); } while (0)
; #define PG8_WAIT_V(n) asm volatile("s_waitcnt vmcnt(" #n ")" ::: "memory")
; #define PG8_WAIT_L(n) asm volatile("s_waitcnt lgkmcnt(" #n ")" ::: "memory")
; #define PG8_BAR __builtin_amdgcn_s_barrier()
; #define PG8_SCHED __builtin_amdgcn_sched_barrier(0)
; template <class Epi, class Sched, bool ALIGN_EPI = false, bool SP2 = false, bool HALO = false>
; __device__ __forceinline__ void gemm_phase(PG8_LAS unsigned char* lds, const Gemm g, const Sched& S, const Epi& E, const int wave0) {
;     ...
;             PG8_LDA(At, 1, 1); PG8_STAGE(PG8_SB(1, 0), b3, voffB); PG8_STAGE(PG8_SB(1, 1), b3 + hstep, voffB); PG8_STAGE(PG8_SA(1, 0), a3, voffA);
;             PG8_WAIT_V(8); PG8_WAIT_L(0); PG8_BAR; PG8_MMA(1, 0, At, B0); PG8_MMA(1, 1, At, B1); PG8_BAR; PG8_SCHED;
;     ...
;         if constexpr (ALIGN_EPI) { if (wr == 0) PG8_BAR; }
	s_add_i32 s44, s70, s81
	v_lshl_add_u64 v[192:193], v[192:193], 0, s[20:21]
	s_mov_b32 m0, s44
	ds_read_b128 v[176:179], v199 offset:49152
	ds_read_b128 v[180:183], v199 offset:50176
	ds_read_b128 v[184:187], v199 offset:51200
	ds_read_b128 v[188:191], v199 offset:52224
	ds_read_b128 v[200:203], v199 offset:53248
	ds_read_b128 v[204:207], v199 offset:54272
	ds_read_b128 v[210:213], v199 offset:55296
	ds_read_b128 v[244:247], v199 offset:56320
	global_load_lds_dwordx4 v[192:193], off
	s_add_i32 m0, s44, 0x2000
	s_add_u32 s14, s14, 0x40080
	v_lshl_add_u64 v[192:193], v[214:215], 0, s[20:21]
	s_addc_u32 s15, s15, 0
	s_add_i32 s44, s71, s81
	global_load_lds_dwordx4 v[192:193], off
	v_lshl_add_u64 v[192:193], s[14:15], 0, v[146:147]
	s_mov_b32 m0, s44
	s_nop 0
	global_load_lds_dwordx4 v[192:193], off
	v_lshl_add_u64 v[192:193], s[14:15], 0, v[150:151]
	s_add_i32 m0, s44, 0x2000
	s_nop 0
	global_load_lds_dwordx4 v[192:193], off
	v_lshl_add_u64 v[192:193], v[248:249], 0, s[20:21]
	s_mov_b32 m0, s61
	s_nop 0
	global_load_lds_dwordx4 v[192:193], off
	v_lshl_add_u64 v[192:193], v[250:251], 0, s[20:21]
	s_mov_b32 m0, s6
	s_nop 0
	global_load_lds_dwordx4 v[192:193], off
	s_waitcnt vmcnt(8)
	s_waitcnt lgkmcnt(0)
	s_barrier
	s_setprio 1
	s_waitcnt lgkmcnt(0)
	v_mfma_f32_16x16x32_bf16 v[76:79], v[56:59], v[176:179], v[76:79]
	v_mfma_f32_16x16x32_bf16 v[72:75], v[64:67], v[176:179], v[72:75]
	v_mfma_f32_16x16x32_bf16 v[44:47], v[56:59], v[184:187], v[44:47]
	v_mfma_f32_16x16x32_bf16 v[40:43], v[64:67], v[184:187], v[40:43]
	v_mfma_f32_16x16x32_bf16 v[28:31], v[56:59], v[200:203], v[28:31]
	v_mfma_f32_16x16x32_bf16 v[24:27], v[64:67], v[200:203], v[24:27]
	v_mfma_f32_16x16x32_bf16 v[12:15], v[56:59], v[210:213], v[12:15]
	v_mfma_f32_16x16x32_bf16 v[8:11], v[64:67], v[210:213], v[8:11]
	v_mfma_f32_16x16x32_bf16 v[76:79], v[60:63], v[180:183], v[76:79]
	v_mfma_f32_16x16x32_bf16 v[72:75], v[68:71], v[180:183], v[72:75]
	v_mfma_f32_16x16x32_bf16 v[44:47], v[60:63], v[188:191], v[44:47]
	v_mfma_f32_16x16x32_bf16 v[40:43], v[68:71], v[188:191], v[40:43]
	v_mfma_f32_16x16x32_bf16 v[28:31], v[60:63], v[204:207], v[28:31]
	v_mfma_f32_16x16x32_bf16 v[24:27], v[68:71], v[204:207], v[24:27]
	v_mfma_f32_16x16x32_bf16 v[12:15], v[60:63], v[244:247], v[12:15]
	v_mfma_f32_16x16x32_bf16 v[8:11], v[68:71], v[244:247], v[8:11]
	s_setprio 0
	s_setprio 1
	v_mfma_f32_16x16x32_bf16 v[48:51], v[160:163], v[176:179], v[48:51]
	v_mfma_f32_16x16x32_bf16 v[68:71], v[164:167], v[180:183], v[48:51]
	v_mfma_f32_16x16x32_bf16 v[48:51], v[168:171], v[176:179], v[52:55]
	v_mfma_f32_16x16x32_bf16 v[36:39], v[160:163], v[184:187], v[36:39]
	v_mfma_f32_16x16x32_bf16 v[32:35], v[168:171], v[184:187], v[32:35]
	v_mfma_f32_16x16x32_bf16 v[20:23], v[160:163], v[200:203], v[20:23]
	v_mfma_f32_16x16x32_bf16 v[16:19], v[168:171], v[200:203], v[16:19]
	v_mfma_f32_16x16x32_bf16 v[4:7], v[160:163], v[210:213], v[4:7]
	v_mfma_f32_16x16x32_bf16 v[0:3], v[168:171], v[210:213], v[0:3]
	v_mfma_f32_16x16x32_bf16 v[64:67], v[172:175], v[180:183], v[48:51]
	v_mfma_f32_16x16x32_bf16 v[36:39], v[164:167], v[188:191], v[36:39]
	v_mfma_f32_16x16x32_bf16 v[32:35], v[172:175], v[188:191], v[32:35]
	v_mfma_f32_16x16x32_bf16 v[20:23], v[164:167], v[204:207], v[20:23]
	v_mfma_f32_16x16x32_bf16 v[16:19], v[172:175], v[204:207], v[16:19]
	v_mfma_f32_16x16x32_bf16 v[4:7], v[164:167], v[244:247], v[4:7]
	v_mfma_f32_16x16x32_bf16 v[0:3], v[172:175], v[244:247], v[0:3]
	s_setprio 0
	s_barrier
	s_add_i32 s67, s67, 2
	s_add_u32 s41, s41, 0x100
	s_addc_u32 s66, s66, 0
	s_add_u32 s42, s42, 0x100
	s_addc_u32 s43, s43, 0
	s_cmp_gt_u32 s67, 13
	s_cbranch_scc0 .LBB0_278
	s_and_b64 vcc, exec, s[68:69]
	s_cbranch_vccz .LBB0_281
	s_barrier

; #define PG8_STAGE(bufoff, gbase, voff) do { _Pragma("unroll") for (int _i = 0; _i < 2; ++_i) \
;         __builtin_amdgcn_global_load_lds((const unsigned*)((const char*)(gbase) + (voff)[_i]), (PG8_LAS unsigned*)(lds + (bufoff) + ldsw + _i * 8192), 16, 0, 0); } while (0)
; #define PG8_LDA(dst, b, h) do { _Pragma("unroll") for (int m = 0; m < 4; ++m) _Pragma("unroll") for (int k = 0; k < 2; ++k) dst[m][k] = *(const PG8_LAS bf16x8*)(lds + PG8_SA(b, h) + aoff + m * 2048 + k * 1024); } while (0)
; #define PG8_LDB(dst, b, h) do { _Pragma("unroll") for (int n = 0; n < 2; ++n) _Pragma("unroll") for (int k = 0; k < 2; ++k) dst[n][k] = *(const PG8_LAS bf16x8*)(lds + PG8_SB(b, h) + boff + n * 2048 + k * 1024); } while (0)
; #define PG8_WAIT_V(n) asm volatile("s_waitcnt vmcnt(" #n ")" ::: "memory")
; #define PG8_WAIT_L(n) asm volatile("s_waitcnt lgkmcnt(" #n ")" ::: "memory")
; #define PG8_BAR __builtin_amdgcn_s_barrier()
; template <class Epi, class Sched, bool ALIGN_EPI = false, bool SP2 = false, bool HALO = false>
; __device__ __forceinline__ void gemm_phase(PG8_LAS unsigned char* lds, const Gemm g, const Sched& S, const Epi& E, const int wave0) {
;     ...
;         const bool has_next = S.next(ui + 1, nxt);
;         const char* nA = has_next ? (const char*)g.A + (size_t)nxt.pm * tstepA : cA; const char* nB = has_next ? (const char*)g.Bt + (size_t)nxt.pn * tstep : cB;
;         for (int t = 0; t < nt; t += 2) {
;             const bool last = (t == nt - 2);
;             const char* a1 = cA + (size_t)(t + 1) * kstep;
;             const char* a2 = last ? nA : cA + (size_t)(t + 2) * kstep; const char* b2 = last ? nB : cB + (size_t)(t + 2) * kstep;
;             const char* a3 = a2 + kstep; const char* b3 = b2 + kstep;
;             if (last && has_next) S.a_ready(nxt);
;             if constexpr (SP2) {
;             PG8_LDB(B0, 0, 0); PG8_LDB(B1, 0, 1); PG8_SCHED; PG8_LDA(At, 0, 0); PG8_STAGE(PG8_SA(1, 1), a1 + hstepA, voffA);
;             PG8_WAIT_V(8); PG8_WAIT_L(0); PG8_BAR; PG8_MMA(0, 0, At, B0); PG8_MMA(0, 1, At, B1); PG8_BAR; PG8_SCHED;
;     ...
;         for (int a = 0; a < 2; ++a)
; #pragma unroll
;             for (int b = 0; b < 2; ++b)
; #pragma unroll
;                 for (int m = 0; m < 4; ++m)
; #pragma unroll
;                     for (int n = 0; n < 2; ++n) acc[a][b][m][n] = (f32x4){0.f, 0.f, 0.f, 0.f};
;         cur = nxt; cA = nA; cB = nB; ++ui;
.LBB0_1080:
	s_ashr_i32 s73, s72, 31
	s_lshl_b64 s[76:77], s[72:73], 19
	s_add_u32 s76, s35, s76
	s_addc_u32 s77, s87, s77
	s_and_b64 s[48:49], s[48:49], exec
	s_cselect_b32 s53, s77, s81
	s_cselect_b32 s73, s76, s80
	s_add_u32 vcc_lo, s80, 0x100
	s_addc_u32 vcc_hi, s81, 0
	s_add_u32 s48, s84, 0x3e080
	v_mov_b32_e32 v0, 0
	s_addc_u32 s49, s85, 0
	s_mov_b32 s78, -2
	v_mov_b32_e32 v1, v0
	v_mov_b32_e32 v2, v0
	v_mov_b32_e32 v3, v0
	v_mov_b32_e32 v4, v0
	v_mov_b32_e32 v5, v0
	v_mov_b32_e32 v6, v0
	v_mov_b32_e32 v7, v0
	v_mov_b32_e32 v16, v0
	v_mov_b32_e32 v17, v0
	v_mov_b32_e32 v18, v0
	v_mov_b32_e32 v19, v0
	v_mov_b32_e32 v20, v0
	v_mov_b32_e32 v21, v0
	v_mov_b32_e32 v22, v0
	v_mov_b32_e32 v23, v0
	v_mov_b32_e32 v32, v0
	v_mov_b32_e32 v33, v0
	v_mov_b32_e32 v34, v0
	v_mov_b32_e32 v35, v0
	v_mov_b32_e32 v36, v0
	v_mov_b32_e32 v37, v0
	v_mov_b32_e32 v38, v0
	v_mov_b32_e32 v39, v0
	v_mov_b32_e32 v48, v0
	v_mov_b32_e32 v49, v0
	v_mov_b32_e32 v50, v0
	v_mov_b32_e32 v51, v0
	v_mov_b32_e32 v52, v0
	v_mov_b32_e32 v53, v0
	v_mov_b32_e32 v54, v0
	v_mov_b32_e32 v55, v0
	v_mov_b32_e32 v8, v0
	v_mov_b32_e32 v9, v0
	v_mov_b32_e32 v10, v0
	v_mov_b32_e32 v11, v0
	v_mov_b32_e32 v12, v0
	v_mov_b32_e32 v13, v0
	v_mov_b32_e32 v14, v0
	v_mov_b32_e32 v15, v0
	v_mov_b32_e32 v24, v0
	v_mov_b32_e32 v25, v0
	v_mov_b32_e32 v26, v0
	v_mov_b32_e32 v27, v0
	v_mov_b32_e32 v28, v0
	v_mov_b32_e32 v29, v0
	v_mov_b32_e32 v30, v0
	v_mov_b32_e32 v31, v0
	v_mov_b32_e32 v40, v0
	v_mov_b32_e32 v41, v0
	v_mov_b32_e32 v42, v0
	v_mov_b32_e32 v43, v0
	v_mov_b32_e32 v44, v0
	v_mov_b32_e32 v45, v0
	v_mov_b32_e32 v46, v0
	v_mov_b32_e32 v47, v0
	v_mov_b32_e32 v88, v0
	v_mov_b32_e32 v89, v0
	v_mov_b32_e32 v90, v0
	v_mov_b32_e32 v91, v0
	v_mov_b32_e32 v72, v0
	v_mov_b32_e32 v73, v0
	v_mov_b32_e32 v74, v0
	v_mov_b32_e32 v75, v0
	v_mov_b32_e32 v96, v0
	v_mov_b32_e32 v97, v0
	v_mov_b32_e32 v98, v0
	v_mov_b32_e32 v99, v0
	v_mov_b32_e32 v100, v0
	v_mov_b32_e32 v101, v0
	v_mov_b32_e32 v102, v0
	v_mov_b32_e32 v103, v0
	v_mov_b32_e32 v112, v0
	v_mov_b32_e32 v113, v0
	v_mov_b32_e32 v114, v0
	v_mov_b32_e32 v115, v0
	v_mov_b32_e32 v116, v0
	v_mov_b32_e32 v117, v0
	v_mov_b32_e32 v118, v0
	v_mov_b32_e32 v119, v0
	v_mov_b32_e32 v128, v0
	v_mov_b32_e32 v129, v0
	v_mov_b32_e32 v130, v0
	v_mov_b32_e32 v131, v0
	v_mov_b32_e32 v132, v0
	v_mov_b32_e32 v133, v0
	v_mov_b32_e32 v134, v0
	v_mov_b32_e32 v135, v0
	v_mov_b32_e32 v144, v0
	v_mov_b32_e32 v145, v0
	v_mov_b32_e32 v146, v0
	v_mov_b32_e32 v147, v0
	v_mov_b32_e32 v148, v0
	v_mov_b32_e32 v149, v0
	v_mov_b32_e32 v150, v0
	v_mov_b32_e32 v151, v0
	v_mov_b32_e32 v104, v0
	v_mov_b32_e32 v105, v0
	v_mov_b32_e32 v106, v0
	v_mov_b32_e32 v107, v0
	v_mov_b32_e32 v108, v0
	v_mov_b32_e32 v109, v0
	v_mov_b32_e32 v110, v0
	v_mov_b32_e32 v111, v0
	v_mov_b32_e32 v120, v0
	v_mov_b32_e32 v121, v0
	v_mov_b32_e32 v122, v0
	v_mov_b32_e32 v123, v0
	v_mov_b32_e32 v124, v0
	v_mov_b32_e32 v125, v0
	v_mov_b32_e32 v126, v0
	v_mov_b32_e32 v127, v0
	v_mov_b32_e32 v136, v0
	v_mov_b32_e32 v137, v0
	v_mov_b32_e32 v138, v0
	v_mov_b32_e32 v139, v0
	v_mov_b32_e32 v140, v0
	v_mov_b32_e32 v141, v0
	v_mov_b32_e32 v142, v0
	v_mov_b32_e32 v143, v0
	v_mov_b32_e32 v156, v0
	v_mov_b32_e32 v157, v0
	v_mov_b32_e32 v158, v0
	v_mov_b32_e32 v159, v0
	v_mov_b32_e32 v152, v0
	v_mov_b32_e32 v153, v0
	v_mov_b32_e32 v154, v0
	v_mov_b32_e32 v155, v0
	s_waitcnt vmcnt(0)
.LBB0_1081:
	s_add_u32 s80, s48, 0xfffc2080
	s_addc_u32 s81, s49, -1
	s_add_i32 s82, 0, 0x10000
	s_cmp_eq_u32 s78, 12
	s_cselect_b32 s85, s75, s81
	s_cselect_b32 s84, s74, s80
	s_cselect_b32 s81, s53, vcc_hi
	s_cselect_b32 s80, s73, vcc_lo
	s_add_i32 s79, 0, 0x14000
	v_add_u32_e32 v68, s82, v173
	v_add_u32_e32 v92, s79, v173
	ds_read_b128 v[56:59], v68
	ds_read_b128 v[60:63], v68 offset:1024
	ds_read_b128 v[64:67], v68 offset:2048
	ds_read_b128 v[68:71], v68 offset:3072
	ds_read_b128 v[76:79], v92
	ds_read_b128 v[80:83], v92 offset:1024
	ds_read_b128 v[84:87], v92 offset:2048
	ds_read_b128 v[92:95], v92 offset:3072
	v_lshl_add_u64 v[170:171], s[48:49], 0, v[168:169]
	s_add_i32 m0, s90, 0xc000
	ds_read_b128 v[180:183], v178
	ds_read_b128 v[184:187], v178 offset:1024
	ds_read_b128 v[188:191], v178 offset:2048
	ds_read_b128 v[192:195], v178 offset:3072
	ds_read_b128 v[196:199], v178 offset:4096
	ds_read_b128 v[200:203], v178 offset:5120
	ds_read_b128 v[204:207], v178 offset:6144
	ds_read_b128 v[210:213], v178 offset:7168
	global_load_lds_dwordx4 v[170:171], off
	v_lshl_add_u64 v[170:171], s[48:49], 0, v[166:167]
	s_add_i32 m0, s90, 0xe000
	s_nop 0
	global_load_lds_dwordx4 v[170:171], off
	s_waitcnt vmcnt(8)
	s_waitcnt lgkmcnt(0)
	s_barrier
; #define PG8_STAGE(bufoff, gbase, voff) do { _Pragma("unroll") for (int _i = 0; _i < 2; ++_i) \
;         __builtin_amdgcn_global_load_lds((const unsigned*)((const char*)(gbase) + (voff)[_i]), (PG8_LAS unsigned*)(lds + (bufoff) + ldsw + _i * 8192), 16, 0, 0); } while (0)
; #define PG8_LDA(dst, b, h) do { _Pragma("unroll") for (int m = 0; m < 4; ++m) _Pragma("unroll") for (int k = 0; k < 2; ++k) dst[m][k] = *(const PG8_LAS bf16x8*)(lds + PG8_SA(b, h) + aoff + m * 2048 + k * 1024); } while (0)
; #define PG8_MMA(ai, bj, At, Bt) do { __builtin_amdgcn_s_setprio(1); _Pragma("unroll") for (int m = 0; m < 4; ++m) _Pragma("unroll") for (int n = 0; n < 2; ++n) _Pragma("unroll") for (int k = 0; k < 2; ++k) \
;         acc[ai][bj][m][n] = __builtin_amdgcn_mfma_f32_16x16x32_bf16(Bt[n][k], At[m][k], acc[ai][bj][m][n], 0, 0, 0); __builtin_amdgcn_s_setprio(0); } while (0)
; #define PG8_WAIT_V(n) asm volatile("s_waitcnt vmcnt(" #n ")" ::: "memory")
; #define PG8_WAIT_L(n) asm volatile("s_waitcnt lgkmcnt(" #n ")" ::: "memory")
; #define PG8_BAR __builtin_amdgcn_s_barrier()
; #define PG8_SCHED __builtin_amdgcn_sched_barrier(0)
; template <class Epi, class Sched, bool ALIGN_EPI = false, bool SP2 = false, bool HALO = false>
; __device__ __forceinline__ void gemm_phase(PG8_LAS unsigned char* lds, const Gemm g, const Sched& S, const Epi& E, const int wave0) {
;     ...
;             PG8_WAIT_V(8); PG8_WAIT_L(0); PG8_BAR; PG8_MMA(0, 0, At, B0); PG8_MMA(0, 1, At, B1); PG8_BAR; PG8_SCHED;
;             PG8_LDA(At, 0, 1); PG8_STAGE(PG8_SB(0, 0), b2, voffB); PG8_STAGE(PG8_SB(0, 1), b2 + hstep, voffB); PG8_STAGE(PG8_SA(0, 0), a2, voffA);
;             PG8_WAIT_V(8); PG8_WAIT_L(0); PG8_BAR; PG8_MMA(1, 0, At, B0); PG8_MMA(1, 1, At, B1); PG8_BAR; PG8_SCHED;
	s_setprio 1
	s_waitcnt lgkmcnt(0)
	v_mfma_f32_16x16x32_bf16 v[152:155], v[56:59], v[180:183], v[152:155]
	v_mfma_f32_16x16x32_bf16 v[156:159], v[64:67], v[180:183], v[156:159]
	v_mfma_f32_16x16x32_bf16 v[140:143], v[56:59], v[188:191], v[140:143]
	v_mfma_f32_16x16x32_bf16 v[136:139], v[64:67], v[188:191], v[136:139]
	v_mfma_f32_16x16x32_bf16 v[124:127], v[56:59], v[196:199], v[124:127]
	v_mfma_f32_16x16x32_bf16 v[120:123], v[64:67], v[196:199], v[120:123]
	v_mfma_f32_16x16x32_bf16 v[108:111], v[56:59], v[204:207], v[108:111]
	v_mfma_f32_16x16x32_bf16 v[104:107], v[64:67], v[204:207], v[104:107]
	v_mfma_f32_16x16x32_bf16 v[152:155], v[60:63], v[184:187], v[152:155]
	v_mfma_f32_16x16x32_bf16 v[156:159], v[68:71], v[184:187], v[156:159]
	v_mfma_f32_16x16x32_bf16 v[140:143], v[60:63], v[192:195], v[140:143]
	v_mfma_f32_16x16x32_bf16 v[136:139], v[68:71], v[192:195], v[136:139]
	v_mfma_f32_16x16x32_bf16 v[124:127], v[60:63], v[200:203], v[124:127]
	v_mfma_f32_16x16x32_bf16 v[120:123], v[68:71], v[200:203], v[120:123]
	v_mfma_f32_16x16x32_bf16 v[108:111], v[60:63], v[210:213], v[108:111]
	v_mfma_f32_16x16x32_bf16 v[104:107], v[68:71], v[210:213], v[104:107]
	s_setprio 0
	s_setprio 1
	v_mfma_f32_16x16x32_bf16 v[148:151], v[76:79], v[180:183], v[148:151]
	v_mfma_f32_16x16x32_bf16 v[144:147], v[84:87], v[180:183], v[144:147]
	v_mfma_f32_16x16x32_bf16 v[132:135], v[76:79], v[188:191], v[132:135]
	v_mfma_f32_16x16x32_bf16 v[128:131], v[84:87], v[188:191], v[128:131]
	v_mfma_f32_16x16x32_bf16 v[116:119], v[76:79], v[196:199], v[116:119]
	v_mfma_f32_16x16x32_bf16 v[112:115], v[84:87], v[196:199], v[112:115]
	v_mfma_f32_16x16x32_bf16 v[100:103], v[76:79], v[204:207], v[100:103]
	v_mfma_f32_16x16x32_bf16 v[96:99], v[84:87], v[204:207], v[96:99]
	v_mfma_f32_16x16x32_bf16 v[148:151], v[80:83], v[184:187], v[148:151]
	v_mfma_f32_16x16x32_bf16 v[144:147], v[92:95], v[184:187], v[144:147]
	v_mfma_f32_16x16x32_bf16 v[132:135], v[80:83], v[192:195], v[132:135]
	v_mfma_f32_16x16x32_bf16 v[128:131], v[92:95], v[192:195], v[128:131]
	v_mfma_f32_16x16x32_bf16 v[116:119], v[80:83], v[200:203], v[116:119]
	v_mfma_f32_16x16x32_bf16 v[112:115], v[92:95], v[200:203], v[112:115]
	v_mfma_f32_16x16x32_bf16 v[100:103], v[80:83], v[210:213], v[100:103]
	v_mfma_f32_16x16x32_bf16 v[96:99], v[92:95], v[210:213], v[96:99]
	s_setprio 0
	s_barrier
	s_add_i32 s82, s82, s89
	v_lshl_add_u64 v[170:171], s[80:81], 0, v[208:209]
	s_mov_b32 m0, s82
	ds_read_b128 v[180:183], v178 offset:16384
	ds_read_b128 v[184:187], v178 offset:17408
	ds_read_b128 v[188:191], v178 offset:18432
	ds_read_b128 v[192:195], v178 offset:19456
	ds_read_b128 v[196:199], v178 offset:20480
	ds_read_b128 v[200:203], v178 offset:21504
	ds_read_b128 v[204:207], v178 offset:22528
	ds_read_b128 v[210:213], v178 offset:23552
	global_load_lds_dwordx4 v[170:171], off
	s_add_i32 m0, s82, 0x2000
	s_add_u32 s82, s80, 0x40000
	v_lshl_add_u64 v[214:215], s[80:81], 0, v[164:165]
	s_addc_u32 s83, s81, 0
	s_add_i32 s79, s79, s89
	global_load_lds_dwordx4 v[214:215], off
	v_lshl_add_u64 v[238:239], s[82:83], 0, v[208:209]
	s_mov_b32 m0, s79
	v_lshl_add_u64 v[244:245], s[84:85], 0, v[162:163]
	global_load_lds_dwordx4 v[238:239], off
	v_lshl_add_u64 v[238:239], s[82:83], 0, v[164:165]
	s_add_i32 m0, s79, 0x2000
	s_nop 0
	global_load_lds_dwordx4 v[238:239], off
	v_lshl_add_u64 v[238:239], s[84:85], 0, v[160:161]
	s_mov_b32 m0, s90
	s_nop 0
	global_load_lds_dwordx4 v[238:239], off
	s_mov_b32 m0, s91
	s_nop 0
	global_load_lds_dwordx4 v[244:245], off
	s_waitcnt vmcnt(8)
	s_waitcnt lgkmcnt(0)
	s_barrier
	s_setprio 1
	s_waitcnt lgkmcnt(0)
	v_mfma_f32_16x16x32_bf16 v[72:75], v[56:59], v[180:183], v[72:75]
	v_mfma_f32_16x16x32_bf16 v[88:91], v[64:67], v[180:183], v[88:91]
	v_mfma_f32_16x16x32_bf16 v[44:47], v[56:59], v[188:191], v[44:47]
	v_mfma_f32_16x16x32_bf16 v[40:43], v[64:67], v[188:191], v[40:43]
	v_mfma_f32_16x16x32_bf16 v[28:31], v[56:59], v[196:199], v[28:31]
	v_mfma_f32_16x16x32_bf16 v[24:27], v[64:67], v[196:199], v[24:27]
	v_mfma_f32_16x16x32_bf16 v[12:15], v[56:59], v[204:207], v[12:15]
	v_mfma_f32_16x16x32_bf16 v[8:11], v[64:67], v[204:207], v[8:11]
	v_mfma_f32_16x16x32_bf16 v[72:75], v[60:63], v[184:187], v[72:75]
	v_mfma_f32_16x16x32_bf16 v[88:91], v[68:71], v[184:187], v[88:91]
	v_mfma_f32_16x16x32_bf16 v[44:47], v[60:63], v[192:195], v[44:47]
	v_mfma_f32_16x16x32_bf16 v[40:43], v[68:71], v[192:195], v[40:43]
	v_mfma_f32_16x16x32_bf16 v[28:31], v[60:63], v[200:203], v[28:31]
	v_mfma_f32_16x16x32_bf16 v[24:27], v[68:71], v[200:203], v[24:27]
	v_mfma_f32_16x16x32_bf16 v[12:15], v[60:63], v[210:213], v[12:15]
	v_mfma_f32_16x16x32_bf16 v[8:11], v[68:71], v[210:213], v[8:11]
	s_setprio 0
	s_setprio 1
	v_mfma_f32_16x16x32_bf16 v[52:55], v[76:79], v[180:183], v[52:55]
	v_mfma_f32_16x16x32_bf16 v[48:51], v[84:87], v[180:183], v[48:51]
	v_mfma_f32_16x16x32_bf16 v[36:39], v[76:79], v[188:191], v[36:39]
	v_mfma_f32_16x16x32_bf16 v[32:35], v[84:87], v[188:191], v[32:35]
	v_mfma_f32_16x16x32_bf16 v[20:23], v[76:79], v[196:199], v[20:23]
	v_mfma_f32_16x16x32_bf16 v[16:19], v[84:87], v[196:199], v[16:19]
	v_mfma_f32_16x16x32_bf16 v[4:7], v[76:79], v[204:207], v[4:7]
	v_mfma_f32_16x16x32_bf16 v[0:3], v[84:87], v[204:207], v[0:3]
	v_mfma_f32_16x16x32_bf16 v[52:55], v[80:83], v[184:187], v[52:55]
	v_mfma_f32_16x16x32_bf16 v[48:51], v[92:95], v[184:187], v[48:51]
	v_mfma_f32_16x16x32_bf16 v[36:39], v[80:83], v[192:195], v[36:39]
	v_mfma_f32_16x16x32_bf16 v[32:35], v[92:95], v[192:195], v[32:35]
	v_mfma_f32_16x16x32_bf16 v[20:23], v[80:83], v[200:203], v[20:23]
	v_mfma_f32_16x16x32_bf16 v[16:19], v[92:95], v[200:203], v[16:19]
	v_mfma_f32_16x16x32_bf16 v[4:7], v[80:83], v[210:213], v[4:7]
	v_mfma_f32_16x16x32_bf16 v[0:3], v[92:95], v[210:213], v[0:3]
	s_setprio 0
	s_barrier
; #define PG8_STAGE(bufoff, gbase, voff) do { _Pragma("unroll") for (int _i = 0; _i < 2; ++_i) \
;         __builtin_amdgcn_global_load_lds((const unsigned*)((const char*)(gbase) + (voff)[_i]), (PG8_LAS unsigned*)(lds + (bufoff) + ldsw + _i * 8192), 16, 0, 0); } while (0)
; #define PG8_LDA(dst, b, h) do { _Pragma("unroll") for (int m = 0; m < 4; ++m) _Pragma("unroll") for (int k = 0; k < 2; ++k) dst[m][k] = *(const PG8_LAS bf16x8*)(lds + PG8_SA(b, h) + aoff + m * 2048 + k * 1024); } while (0)
; #define PG8_LDB(dst, b, h) do { _Pragma("unroll") for (int n = 0; n < 2; ++n) _Pragma("unroll") for (int k = 0; k < 2; ++k) dst[n][k] = *(const PG8_LAS bf16x8*)(lds + PG8_SB(b, h) + boff + n * 2048 + k * 1024); } while (0)
; #define PG8_MMA(ai, bj, At, Bt) do { __builtin_amdgcn_s_setprio(1); _Pragma("unroll") for (int m = 0; m < 4; ++m) _Pragma("unroll") for (int n = 0; n < 2; ++n) _Pragma("unroll") for (int k = 0; k < 2; ++k) \
;         acc[ai][bj][m][n] = __builtin_amdgcn_mfma_f32_16x16x32_bf16(Bt[n][k], At[m][k], acc[ai][bj][m][n], 0, 0, 0); __builtin_amdgcn_s_setprio(0); } while (0)
; #define PG8_WAIT_V(n) asm volatile("s_waitcnt vmcnt(" #n ")" ::: "memory")
; #define PG8_WAIT_L(n) asm volatile("s_waitcnt lgkmcnt(" #n ")" ::: "memory")
; #define PG8_BAR __builtin_amdgcn_s_barrier()
; #define PG8_SCHED __builtin_amdgcn_sched_barrier(0)
; template <class Epi, class Sched, bool ALIGN_EPI = false, bool SP2 = false, bool HALO = false>
; __device__ __forceinline__ void gemm_phase(PG8_LAS unsigned char* lds, const Gemm g, const Sched& S, const Epi& E, const int wave0) {
;     ...
;             PG8_LDB(B0, 1, 0); PG8_LDB(B1, 1, 1); PG8_SCHED; PG8_LDA(At, 1, 0); PG8_STAGE(PG8_SA(0, 1), a2 + hstepA, voffA);
;             PG8_WAIT_V(8); PG8_WAIT_L(0); PG8_BAR; PG8_MMA(0, 0, At, B0); PG8_MMA(0, 1, At, B1); PG8_BAR; PG8_SCHED;
	s_add_i32 s79, 0, 0x18000
	s_add_i32 s12, 0, 0x1c000
	v_add_u32_e32 v68, s79, v173
	v_add_u32_e32 v92, s12, v173
	ds_read_b128 v[56:59], v68
	ds_read_b128 v[60:63], v68 offset:1024
	ds_read_b128 v[64:67], v68 offset:2048
	ds_read_b128 v[68:71], v68 offset:3072
	ds_read_b128 v[76:79], v92
	ds_read_b128 v[80:83], v92 offset:1024
	ds_read_b128 v[84:87], v92 offset:2048
	ds_read_b128 v[92:95], v92 offset:3072
	s_add_u32 s82, s84, 0x3e000
	s_addc_u32 s83, s85, 0
	s_mov_b32 m0, s92
	v_lshl_add_u64 v[246:247], s[82:83], 0, v[160:161]
	ds_read_b128 v[180:183], v178 offset:32768
	ds_read_b128 v[184:187], v178 offset:33792
	ds_read_b128 v[188:191], v178 offset:34816
	ds_read_b128 v[192:195], v178 offset:35840
	ds_read_b128 v[196:199], v178 offset:36864
	ds_read_b128 v[200:203], v178 offset:37888
	ds_read_b128 v[204:207], v178 offset:38912
	ds_read_b128 v[210:213], v178 offset:39936
	global_load_lds_dwordx4 v[246:247], off
	v_lshl_add_u64 v[246:247], s[82:83], 0, v[162:163]
	s_mov_b32 m0, s93
	s_nop 0
	global_load_lds_dwordx4 v[246:247], off
	s_waitcnt vmcnt(8)
	s_waitcnt lgkmcnt(0)
	s_barrier
	s_setprio 1
	s_waitcnt lgkmcnt(0)
	v_mfma_f32_16x16x32_bf16 v[152:155], v[56:59], v[180:183], v[152:155]
	v_mfma_f32_16x16x32_bf16 v[156:159], v[64:67], v[180:183], v[156:159]
	v_mfma_f32_16x16x32_bf16 v[140:143], v[56:59], v[188:191], v[140:143]
	v_mfma_f32_16x16x32_bf16 v[136:139], v[64:67], v[188:191], v[136:139]
	v_mfma_f32_16x16x32_bf16 v[124:127], v[56:59], v[196:199], v[124:127]
	v_mfma_f32_16x16x32_bf16 v[120:123], v[64:67], v[196:199], v[120:123]
	v_mfma_f32_16x16x32_bf16 v[108:111], v[56:59], v[204:207], v[108:111]
	v_mfma_f32_16x16x32_bf16 v[104:107], v[64:67], v[204:207], v[104:107]
	v_mfma_f32_16x16x32_bf16 v[152:155], v[60:63], v[184:187], v[152:155]
	v_mfma_f32_16x16x32_bf16 v[156:159], v[68:71], v[184:187], v[156:159]
	v_mfma_f32_16x16x32_bf16 v[140:143], v[60:63], v[192:195], v[140:143]
	v_mfma_f32_16x16x32_bf16 v[136:139], v[68:71], v[192:195], v[136:139]
	v_mfma_f32_16x16x32_bf16 v[124:127], v[60:63], v[200:203], v[124:127]
	v_mfma_f32_16x16x32_bf16 v[120:123], v[68:71], v[200:203], v[120:123]
	v_mfma_f32_16x16x32_bf16 v[108:111], v[60:63], v[210:213], v[108:111]
	v_mfma_f32_16x16x32_bf16 v[104:107], v[68:71], v[210:213], v[104:107]
	s_setprio 0
	s_setprio 1
	v_mfma_f32_16x16x32_bf16 v[148:151], v[76:79], v[180:183], v[148:151]
	v_mfma_f32_16x16x32_bf16 v[144:147], v[84:87], v[180:183], v[144:147]
	v_mfma_f32_16x16x32_bf16 v[132:135], v[76:79], v[188:191], v[132:135]
	v_mfma_f32_16x16x32_bf16 v[128:131], v[84:87], v[188:191], v[128:131]
	v_mfma_f32_16x16x32_bf16 v[116:119], v[76:79], v[196:199], v[116:119]
	v_mfma_f32_16x16x32_bf16 v[112:115], v[84:87], v[196:199], v[112:115]
	v_mfma_f32_16x16x32_bf16 v[100:103], v[76:79], v[204:207], v[100:103]
	v_mfma_f32_16x16x32_bf16 v[96:99], v[84:87], v[204:207], v[96:99]
	v_mfma_f32_16x16x32_bf16 v[148:151], v[80:83], v[184:187], v[148:151]
	v_mfma_f32_16x16x32_bf16 v[144:147], v[92:95], v[184:187], v[144:147]
	v_mfma_f32_16x16x32_bf16 v[132:135], v[80:83], v[192:195], v[132:135]
	v_mfma_f32_16x16x32_bf16 v[128:131], v[92:95], v[192:195], v[128:131]
	v_mfma_f32_16x16x32_bf16 v[116:119], v[80:83], v[200:203], v[116:119]
	v_mfma_f32_16x16x32_bf16 v[112:115], v[92:95], v[200:203], v[112:115]
	v_mfma_f32_16x16x32_bf16 v[100:103], v[80:83], v[210:213], v[100:103]
	v_mfma_f32_16x16x32_bf16 v[96:99], v[92:95], v[210:213], v[96:99]
	s_setprio 0
	s_barrier
; #define PG8_STAGE(bufoff, gbase, voff) do { _Pragma("unroll") for (int _i = 0; _i < 2; ++_i) \
;         __builtin_amdgcn_global_load_lds((const unsigned*)((const char*)(gbase) + (voff)[_i]), (PG8_LAS unsigned*)(lds + (bufoff) + ldsw + _i * 8192), 16, 0, 0); } while (0)
; #define PG8_LDA(dst, b, h) do { _Pragma("unroll") for (int m = 0; m < 4; ++m) _Pragma("unroll") for (int k = 0; k < 2; ++k) dst[m][k] = *(const PG8_LAS bf16x8*)(lds + PG8_SA(b, h) + aoff + m * 2048 + k * 1024); } while (0)
; #define PG8_MMA(ai, bj, At, Bt) do { __builtin_amdgcn_s_setprio(1); _Pragma("unroll") for (int m = 0; m < 4; ++m) _Pragma("unroll") for (int n = 0; n < 2; ++n) _Pragma("unroll") for (int k = 0; k < 2; ++k) \
;         acc[ai][bj][m][n] = __builtin_amdgcn_mfma_f32_16x16x32_bf16(Bt[n][k], At[m][k], acc[ai][bj][m][n], 0, 0, 0); __builtin_amdgcn_s_setprio(0); } while (0)
; #define PG8_WAIT_V(n) asm volatile("s_waitcnt vmcnt(" #n ")" ::: "memory")
; #define PG8_WAIT_L(n) asm volatile("s_waitcnt lgkmcnt(" #n ")" ::: "memory")
; #define PG8_BAR __builtin_amdgcn_s_barrier()
; #define PG8_SCHED __builtin_amdgcn_sched_barrier(0)
; template <class Epi, class Sched, bool ALIGN_EPI = false, bool SP2 = false, bool HALO = false>
; __device__ __forceinline__ void gemm_phase(PG8_LAS unsigned char* lds, const Gemm g, const Sched& S, const Epi& E, const int wave0) {
;     ...
;             PG8_LDA(At, 1, 1); PG8_STAGE(PG8_SB(1, 0), b3, voffB); PG8_STAGE(PG8_SB(1, 1), b3 + hstep, voffB); PG8_STAGE(PG8_SA(1, 0), a3, voffA);
;             PG8_WAIT_V(8); PG8_WAIT_L(0); PG8_BAR; PG8_MMA(1, 0, At, B0); PG8_MMA(1, 1, At, B1); PG8_BAR; PG8_SCHED;
;     ...
;         if constexpr (ALIGN_EPI) { if (wr == 0) PG8_BAR; }
	s_add_i32 s79, s79, s89
	v_lshl_add_u64 v[170:171], v[170:171], 0, s[20:21]
	s_mov_b32 m0, s79
	ds_read_b128 v[180:183], v178 offset:49152
	ds_read_b128 v[184:187], v178 offset:50176
	ds_read_b128 v[188:191], v178 offset:51200
	ds_read_b128 v[192:195], v178 offset:52224
	ds_read_b128 v[196:199], v178 offset:53248
	ds_read_b128 v[200:203], v178 offset:54272
	ds_read_b128 v[204:207], v178 offset:55296
	ds_read_b128 v[210:213], v178 offset:56320
	global_load_lds_dwordx4 v[170:171], off
	s_add_i32 m0, s79, 0x2000
	s_add_u32 s80, s80, 0x40080
	v_lshl_add_u64 v[170:171], v[214:215], 0, s[20:21]
	s_addc_u32 s81, s81, 0
	s_add_i32 s12, s12, s89
	global_load_lds_dwordx4 v[170:171], off
	v_lshl_add_u64 v[170:171], s[80:81], 0, v[208:209]
	s_mov_b32 m0, s12
	s_nop 0
	global_load_lds_dwordx4 v[170:171], off
	v_lshl_add_u64 v[170:171], s[80:81], 0, v[164:165]
	s_add_i32 m0, s12, 0x2000
	s_nop 0
	global_load_lds_dwordx4 v[170:171], off
	v_lshl_add_u64 v[170:171], v[238:239], 0, s[20:21]
	s_mov_b32 m0, s94
	s_nop 0
	global_load_lds_dwordx4 v[170:171], off
	v_lshl_add_u64 v[170:171], v[244:245], 0, s[20:21]
	s_mov_b32 m0, s95
	s_nop 0
	global_load_lds_dwordx4 v[170:171], off
	s_waitcnt vmcnt(8)
	s_waitcnt lgkmcnt(0)
	s_barrier
	s_setprio 1
	s_waitcnt lgkmcnt(0)
	v_mfma_f32_16x16x32_bf16 v[72:75], v[56:59], v[180:183], v[72:75]
	v_mfma_f32_16x16x32_bf16 v[88:91], v[64:67], v[180:183], v[88:91]
	v_mfma_f32_16x16x32_bf16 v[44:47], v[56:59], v[188:191], v[44:47]
	v_mfma_f32_16x16x32_bf16 v[40:43], v[64:67], v[188:191], v[40:43]
	v_mfma_f32_16x16x32_bf16 v[28:31], v[56:59], v[196:199], v[28:31]
	v_mfma_f32_16x16x32_bf16 v[24:27], v[64:67], v[196:199], v[24:27]
	v_mfma_f32_16x16x32_bf16 v[12:15], v[56:59], v[204:207], v[12:15]
	v_mfma_f32_16x16x32_bf16 v[8:11], v[64:67], v[204:207], v[8:11]
	v_mfma_f32_16x16x32_bf16 v[72:75], v[60:63], v[184:187], v[72:75]
	v_mfma_f32_16x16x32_bf16 v[88:91], v[68:71], v[184:187], v[88:91]
	v_mfma_f32_16x16x32_bf16 v[44:47], v[60:63], v[192:195], v[44:47]
	v_mfma_f32_16x16x32_bf16 v[40:43], v[68:71], v[192:195], v[40:43]
	v_mfma_f32_16x16x32_bf16 v[28:31], v[60:63], v[200:203], v[28:31]
	v_mfma_f32_16x16x32_bf16 v[24:27], v[68:71], v[200:203], v[24:27]
	v_mfma_f32_16x16x32_bf16 v[12:15], v[60:63], v[210:213], v[12:15]
	v_mfma_f32_16x16x32_bf16 v[8:11], v[68:71], v[210:213], v[8:11]
	s_setprio 0
	s_setprio 1
	v_mfma_f32_16x16x32_bf16 v[52:55], v[76:79], v[180:183], v[52:55]
	v_mfma_f32_16x16x32_bf16 v[48:51], v[84:87], v[180:183], v[48:51]
	v_mfma_f32_16x16x32_bf16 v[36:39], v[76:79], v[188:191], v[36:39]
	v_mfma_f32_16x16x32_bf16 v[32:35], v[84:87], v[188:191], v[32:35]
	v_mfma_f32_16x16x32_bf16 v[20:23], v[76:79], v[196:199], v[20:23]
	v_mfma_f32_16x16x32_bf16 v[16:19], v[84:87], v[196:199], v[16:19]
	v_mfma_f32_16x16x32_bf16 v[4:7], v[76:79], v[204:207], v[4:7]
	v_mfma_f32_16x16x32_bf16 v[0:3], v[84:87], v[204:207], v[0:3]
	v_mfma_f32_16x16x32_bf16 v[52:55], v[80:83], v[184:187], v[52:55]
	v_mfma_f32_16x16x32_bf16 v[48:51], v[92:95], v[184:187], v[48:51]
	v_mfma_f32_16x16x32_bf16 v[36:39], v[80:83], v[192:195], v[36:39]
	v_mfma_f32_16x16x32_bf16 v[32:35], v[92:95], v[192:195], v[32:35]
	v_mfma_f32_16x16x32_bf16 v[20:23], v[80:83], v[200:203], v[20:23]
	v_mfma_f32_16x16x32_bf16 v[16:19], v[92:95], v[200:203], v[16:19]
	v_mfma_f32_16x16x32_bf16 v[4:7], v[80:83], v[210:213], v[4:7]
	v_mfma_f32_16x16x32_bf16 v[0:3], v[92:95], v[210:213], v[0:3]
	s_setprio 0
	s_barrier
	s_add_i32 s78, s78, 2
	s_add_u32 vcc_lo, vcc_lo, 0x100
	s_addc_u32 vcc_hi, vcc_hi, 0
	s_add_u32 s48, s48, 0x100
	s_addc_u32 s49, s49, 0
	s_cmp_gt_u32 s78, 13
	s_cbranch_scc0 .LBB0_1081
	s_and_b64 vcc, exec, s[60:61]
	s_cbranch_vccz .LBB0_1084
	s_barrier
